# prompt attention: trailing re-load DMA drain moved from before the last tile to the barrier that frees LDS for the unit epilogue, size-neutral (later code keeps its byte placement)
# speedup vs baseline: 1.0190x; 1.0074x over previous
; #define SBAR() __builtin_amdgcn_sched_barrier(0)
; #define FIN(P0, P1) do { PK4(P0, 0, pa0); PK4(P0, 8, pa1); PK4(P1, 0, pa2); PK4(P1, 8, pa3); } while (0)
; __device__ __forceinline__ void attn_prompt(Frame& F, int b, int h, int qb, float lam, float mshift) {
;     ...
;     asm volatile("s_waitcnt vmcnt(0)" ::: "memory");
;     SBAR(); if (vis) { QKT(pB0, pB1, s_cur, NT - 1); } FIN(pA0, pA1); SBAR();
.LBB0_517:
	s_cmp_lg_u32 s83, s2
	s_cselect_b64 s[0:1], -1, 0
	s_cmp_eq_u32 s83, s2
	s_cbranch_scc0 .LBB0_519
	s_lshl_b32 s2, s2, 6
	v_sub_u32_e32 v90, s2, v201
	s_add_i32 s3, s65, 0
	v_lshlrev_b32_e32 v90, 2, v90
	s_add_i32 s2, 0, 0x20400
	v_add_u32_e32 v86, s3, v200
	v_add3_u32 v90, s2, v90, v194
	ds_read_b128 v[82:85], v86
	ds_read_b128 v[86:89], v86 offset:8192
	ds_read2_b32 v[114:115], v90 offset0:191 offset1:192
	ds_read2_b32 v[116:117], v90 offset0:193 offset1:194
	ds_read2_b32 v[118:119], v90 offset0:199 offset1:200
	ds_read2_b32 v[120:121], v90 offset0:201 offset1:202
	ds_read2_b32 v[122:123], v90 offset0:207 offset1:208
	ds_read2_b32 v[124:125], v90 offset0:209 offset1:210
	ds_read2_b32 v[126:127], v90 offset0:215 offset1:216
	ds_read2_b32 v[128:129], v90 offset0:217 offset1:218
	ds_read2_b32 v[98:99], v90 offset0:223 offset1:224
	ds_read2_b32 v[100:101], v90 offset0:225 offset1:226
	ds_read2_b32 v[102:103], v90 offset0:231 offset1:232
	ds_read2_b32 v[104:105], v90 offset0:233 offset1:234
	ds_read2_b32 v[106:107], v90 offset0:239 offset1:240
	ds_read2_b32 v[108:109], v90 offset0:241 offset1:242
	ds_read2_b32 v[110:111], v90 offset0:247 offset1:248
	ds_read2_b32 v[112:113], v90 offset0:249 offset1:250
	s_waitcnt lgkmcnt(8)
	v_mfma_f32_32x32x16_bf16 v[114:129], v[82:85], v[174:177], v[114:129]
	v_add_u32_e32 v90, s3, v195
	s_waitcnt lgkmcnt(0)
	v_mfma_f32_32x32x16_bf16 v[98:113], v[86:89], v[174:177], v[98:113]
	v_add_u32_e32 v86, v90, v202
	ds_read_b128 v[82:85], v86
	ds_read_b128 v[86:89], v86 offset:8192
	s_waitcnt lgkmcnt(1)
	v_mfma_f32_32x32x16_bf16 v[114:129], v[82:85], v[170:173], v[114:129]
	s_waitcnt lgkmcnt(0)
	v_mfma_f32_32x32x16_bf16 v[98:113], v[86:89], v[170:173], v[98:113]
	v_add_u32_e32 v86, v90, v203
	ds_read_b128 v[82:85], v86
	ds_read_b128 v[86:89], v86 offset:8192
	s_waitcnt lgkmcnt(1)
	v_mfma_f32_32x32x16_bf16 v[114:129], v[82:85], v[166:169], v[114:129]
	s_waitcnt lgkmcnt(0)
	v_mfma_f32_32x32x16_bf16 v[98:113], v[86:89], v[166:169], v[98:113]
	v_add_u32_e32 v86, v90, v204
	ds_read_b128 v[82:85], v86
	ds_read_b128 v[86:89], v86 offset:8192
	s_waitcnt lgkmcnt(1)
	v_mfma_f32_32x32x16_bf16 v[114:129], v[82:85], v[162:165], v[114:129]
	s_waitcnt lgkmcnt(0)
	v_mfma_f32_32x32x16_bf16 v[98:113], v[86:89], v[162:165], v[98:113]
